# tile headers: next tile (pm,pn) derived incrementally from the current tile instead of two integer divisions
# speedup vs baseline: 1.0107x; 1.0022x over previous
;     __device__ bool next(int i, Unit& u) const {
;         const long L = (long)i * G + c; if (L >= nwg) return false;
;         int wgid = (int)L; { const int q = nwg / NXCD, r = nwg % NXCD, xcd = wgid % NXCD, off = wgid / NXCD; wgid = (xcd < r ? xcd * (q + 1) : r * (q + 1) + (xcd - r) * q) + off; }
;         const int nig = WGM * nN, gid = wgid / nig, fm = gid * WGM, gsz = (nM - fm) < WGM ? (nM - fm) : WGM;
;         u.pm = fm + ((wgid % nig) % gsz); u.pn = (wgid % nig) / gsz; return true;
; template <class Epi, bool ALIGN_EPI>
; __device__ __forceinline__ void gemm_phase(LAS unsigned char* lds, const Gemm g, const StaticOrder& S, const Epi& E, const int tid) {
;     ...
;         const bool has_next = S.next(ui + 1, nxt);
.LBB0_228:
	s_add_i32 s64, s64, 1
	s_mul_i32 s10, s64, s61
	s_mul_hi_u32 s11, s64, s6
	s_add_i32 s11, s11, s10
	s_mul_i32 s10, s64, s6
	s_add_u32 s14, s10, s0
	s_addc_u32 s15, s11, s62
	s_waitcnt lgkmcnt(0)
	v_mov_b64_e32 v[0:1], s[38:39]
	v_cmp_ge_i64_e64 s[10:11], s[14:15], v[0:1]
	v_cmp_lt_i64_e64 s[12:13], s[14:15], v[0:1]
	s_and_b64 vcc, exec, s[10:11]
	s_cbranch_vccnz .LBB0_230
	s_and_b32 s14, s69, 7
	s_lshl_b32 s15, s68, 3
	s_add_i32 s14, s14, s15
	s_lshr_b32 s15, s6, 3
	s_add_i32 s14, s14, s15
	s_and_b32 s67, s69, -8
	s_sub_i32 s15, s14, s59
	s_cmp_ge_u32 s14, s59
	s_cselect_b32 s14, s15, s14
	s_cselect_b32 s15, 8, 0
	s_add_i32 s67, s67, s15
	s_lshr_b32 s66, s14, 3
	s_and_b32 s14, s14, 7
	s_add_i32 s67, s67, s14
	v_readlane_b32 s70, v255, 47
	s_mov_b32 s72, 0x40000
	s_mov_b32 s73, 0x6c80000
	v_readlane_b32 s71, v255, 48

;     __device__ bool next(int i, Unit& u) const {
;         const long L = (long)i * G + c; if (L >= nwg) return false;
;         int wgid = (int)L; { const int q = nwg / NXCD, r = nwg % NXCD, xcd = wgid % NXCD, off = wgid / NXCD; wgid = (xcd < r ? xcd * (q + 1) : r * (q + 1) + (xcd - r) * q) + off; }
;         const int nig = WGM * nN, gid = wgid / nig, fm = gid * WGM, gsz = (nM - fm) < WGM ? (nM - fm) : WGM;
;         u.pm = fm + ((wgid % nig) % gsz); u.pn = (wgid % nig) / gsz; return true;
; template <class Epi, bool ALIGN_EPI>
; __device__ __forceinline__ void gemm_phase(LAS unsigned char* lds, const Gemm g, const StaticOrder& S, const Epi& E, const int tid) {
;     ...
;         const bool has_next = S.next(ui + 1, nxt);
.LBB0_266:
	s_add_i32 s62, s62, 1
	s_mul_i32 s8, s62, s58
	s_mul_hi_u32 s9, s62, s6
	s_add_i32 s9, s9, s8
	s_mul_i32 s8, s62, s6
	s_add_u32 s12, s8, s0
	s_addc_u32 s13, s9, s59
	s_waitcnt lgkmcnt(0)
	v_mov_b64_e32 v[0:1], s[38:39]
	v_cmp_ge_i64_e64 s[8:9], s[12:13], v[0:1]
	v_cmp_lt_i64_e64 s[10:11], s[12:13], v[0:1]
	s_and_b64 vcc, exec, s[8:9]
	s_cbranch_vccnz .LBB0_268
	s_and_b32 s12, s67, 7
	s_lshl_b32 s13, s66, 3
	s_add_i32 s12, s12, s13
	s_lshr_b32 s13, s6, 3
	s_add_i32 s12, s12, s13
	s_and_b32 s65, s67, -8
	s_sub_i32 s13, s12, s61
	s_cmp_ge_u32 s12, s61
	s_cselect_b32 s12, s13, s12
	s_cselect_b32 s13, 8, 0
	s_add_i32 s65, s65, s13
	s_lshr_b32 s64, s12, 3
	s_and_b32 s12, s12, 7
	s_add_i32 s65, s65, s12
	s_mov_b32 s72, 0x40000
	s_mov_b64 s[70:71], s[90:91]

;     __device__ bool next(int i, Unit& u) const {
;         const long L = (long)i * G + c; if (L >= nwg) return false;
;         int wgid = (int)L; { const int q = nwg / NXCD, r = nwg % NXCD, xcd = wgid % NXCD, off = wgid / NXCD; wgid = (xcd < r ? xcd * (q + 1) : r * (q + 1) + (xcd - r) * q) + off; }
;         const int nig = WGM * nN, gid = wgid / nig, fm = gid * WGM, gsz = (nM - fm) < WGM ? (nM - fm) : WGM;
;         u.pm = fm + ((wgid % nig) % gsz); u.pn = (wgid % nig) / gsz; return true;
; template <class Epi, bool ALIGN_EPI>
; __device__ __forceinline__ void gemm_phase(LAS unsigned char* lds, const Gemm g, const StaticOrder& S, const Epi& E, const int tid) {
;     ...
;         const bool has_next = S.next(ui + 1, nxt);
.LBB0_300:
	s_add_i32 s60, s60, 1
	s_mul_i32 s8, s60, s59
	s_mul_hi_u32 s9, s60, s6
	s_add_i32 s9, s9, s8
	s_mul_i32 s8, s60, s6
	s_add_u32 s8, s8, s0
	s_addc_u32 s9, s9, s47
	v_mov_b64_e32 v[224:225], s[38:39]
	v_cmp_ge_i64_e32 vcc, s[8:9], v[224:225]
	v_cmp_lt_i64_e64 s[10:11], s[8:9], v[224:225]
	s_cbranch_vccnz .LBB0_302
	s_and_b32 s8, s64, 7
	s_lshl_b32 s9, s63, 3
	s_add_i32 s8, s8, s9
	s_lshr_b32 s9, s6, 3
	s_add_i32 s8, s8, s9
	s_and_b32 s62, s64, -8
	s_sub_i32 s9, s8, s49
	s_cmp_ge_u32 s8, s49
	s_cselect_b32 s8, s9, s8
	s_cselect_b32 s9, 8, 0
	s_add_i32 s62, s62, s9
	s_lshr_b32 s61, s8, 3
	s_and_b32 s8, s8, 7
	s_add_i32 s62, s62, s8
	s_mov_b64 s[70:71], s[90:91]

;     __device__ bool next(int i, Unit& u) const {
;         const long L = (long)i * G + c; if (L >= nwg) return false;
;         int wgid = (int)L; { const int q = nwg / NXCD, r = nwg % NXCD, xcd = wgid % NXCD, off = wgid / NXCD; wgid = (xcd < r ? xcd * (q + 1) : r * (q + 1) + (xcd - r) * q) + off; }
;         const int nig = WGM * nN, gid = wgid / nig, fm = gid * WGM, gsz = (nM - fm) < WGM ? (nM - fm) : WGM;
;         u.pm = fm + ((wgid % nig) % gsz); u.pn = (wgid % nig) / gsz; return true;
; template <class Epi, bool ALIGN_EPI>
; __device__ __forceinline__ void gemm_phase(LAS unsigned char* lds, const Gemm g, const StaticOrder& S, const Epi& E, const int tid) {
;     ...
;         const bool has_next = S.next(ui + 1, nxt);
.LBB0_323:
	s_add_i32 s60, s60, 1
	s_mul_i32 s8, s60, s59
	s_mul_hi_u32 s9, s60, s6
	s_add_i32 s9, s9, s8
	s_mul_i32 s8, s60, s6
	s_add_u32 s8, s8, s0
	s_addc_u32 s9, s9, s47
	v_mov_b64_e32 v[0:1], s[38:39]
	v_cmp_ge_i64_e32 vcc, s[8:9], v[0:1]
	v_cmp_lt_i64_e64 s[10:11], s[8:9], v[0:1]
	s_cbranch_vccnz .LBB0_325
	s_and_b32 s8, s64, 7
	s_lshl_b32 s9, s63, 3
	s_add_i32 s8, s8, s9
	s_lshr_b32 s9, s6, 3
	s_add_i32 s8, s8, s9
	s_and_b32 s62, s64, -8
	s_sub_i32 s9, s8, s49
	s_cmp_ge_u32 s8, s49
	s_cselect_b32 s8, s9, s8
	s_cselect_b32 s9, 8, 0
	s_add_i32 s62, s62, s9
	s_lshr_b32 s61, s8, 3
	s_and_b32 s8, s8, 7
	s_add_i32 s62, s62, s8
	s_mov_b64 s[70:71], s[90:91]

;     __device__ bool next(int i, Unit& u) const {
;         const long L = (long)i * G + c; if (L >= nwg) return false;
;         int wgid = (int)L; { const int q = nwg / NXCD, r = nwg % NXCD, xcd = wgid % NXCD, off = wgid / NXCD; wgid = (xcd < r ? xcd * (q + 1) : r * (q + 1) + (xcd - r) * q) + off; }
;         const int nig = WGM * nN, gid = wgid / nig, fm = gid * WGM, gsz = (nM - fm) < WGM ? (nM - fm) : WGM;
;         u.pm = fm + ((wgid % nig) % gsz); u.pn = (wgid % nig) / gsz; return true;
; template <class Epi, bool ALIGN_EPI>
; __device__ __forceinline__ void gemm_phase(LAS unsigned char* lds, const Gemm g, const StaticOrder& S, const Epi& E, const int tid) {
;     ...
;         const bool has_next = S.next(ui + 1, nxt);
.LBB0_346:
	s_add_i32 s57, s57, 1
	s_mul_i32 s8, s57, s56
	s_mul_hi_u32 s9, s57, s6
	s_add_i32 s9, s9, s8
	s_mul_i32 s8, s57, s6
	s_add_u32 s8, s8, s0
	s_addc_u32 s9, s9, s47
	v_mov_b64_e32 v[224:225], s[38:39]
	v_cmp_ge_i64_e32 vcc, s[8:9], v[224:225]
	v_cmp_lt_i64_e64 s[10:11], s[8:9], v[224:225]
	s_cbranch_vccnz .LBB0_348
	s_and_b32 s8, s61, 7
	s_lshl_b32 s9, s60, 3
	s_add_i32 s8, s8, s9
	s_lshr_b32 s9, s6, 3
	s_add_i32 s8, s8, s9
	s_and_b32 s59, s61, -8
	s_sub_i32 s9, s8, s7
	s_cmp_ge_u32 s8, s7
	s_cselect_b32 s8, s9, s8
	s_cselect_b32 s9, 8, 0
	s_add_i32 s59, s59, s9
	s_lshr_b32 s58, s8, 3
	s_and_b32 s8, s8, 7
	s_add_i32 s59, s59, s8
